# stack1 + GEMM prologue second stage group issued before the first wait
# baseline (speedup 1.0000x reference)
; #define PG8_STAGE(bufoff, gbase, voff) do { _Pragma("unroll") for (int _i = 0; _i < 2; ++_i) \
;         __builtin_amdgcn_global_load_lds((const unsigned*)((const char*)(gbase) + (voff)[_i]), (PG8_LAS unsigned*)(lds + (bufoff) + ldsw + _i * 8192), 16, 0, 0); } while (0)
; #define PG8_WAIT_V(n) asm volatile("s_waitcnt vmcnt(" #n ")" ::: "memory")
; #define PG8_BAR __builtin_amdgcn_s_barrier()
; template <class Epi, class Sched, bool ALIGN_EPI = false, bool SP2 = false>
; __device__ __forceinline__ void gemm_phase(PG8_LAS unsigned char* lds, const Gemm g, const Sched& S, const Epi& E) {
;     ...
;     if constexpr (SP2) {
;         PG8_STAGE(PG8_SB(0, 0), cB, voffB); PG8_STAGE(PG8_SB(0, 1), cB + hstep, voffB); PG8_STAGE(PG8_SA(0, 0), cA, voffA); PG8_STAGE(PG8_SA(0, 1), cA + ahstep, voffA);
;         if (wr == 1) PG8_BAR;
;         PG8_WAIT_V(2); PG8_BAR;
;         PG8_STAGE(PG8_SB(1, 0), cB + kstep, voffB); PG8_STAGE(PG8_SA(1, 0), cA + akstep, voffA); PG8_STAGE(PG8_SB(1, 1), cB + hstep + kstep, voffB);
;         PG8_WAIT_V(6); PG8_BAR;
.LBB0_196:
	s_mov_b64 s[22:23], 0x80
	s_and_b32 s3, s3, 3
	s_add_i32 m0, s45, 0x18000
	v_lshl_add_u64 v[10:11], v[10:11], 0, s[22:23]
	s_lshl_b32 s29, s2, 13
	s_lshl_b32 s46, s3, 12
	global_load_lds_dwordx4 v[10:11], off
	v_lshl_add_u64 v[8:9], v[8:9], 0, s[22:23]
	s_add_i32 m0, s45, 0x1a000
	s_add_i32 s56, s45, 0x8000
	s_add_i32 s57, s45, 0xa000
	global_load_lds_dwordx4 v[8:9], off
	v_lshl_add_u64 v[4:5], v[4:5], 0, s[22:23]
	s_mov_b32 m0, s56
	s_add_u32 s42, s4, 0x40080
	global_load_lds_dwordx4 v[4:5], off
	v_lshl_add_u64 v[4:5], v[6:7], 0, s[22:23]
	s_mov_b32 m0, s57
	s_addc_u32 s43, s5, 0
	global_load_lds_dwordx4 v[4:5], off
	s_add_i32 m0, s45, 0x1c000
	v_lshl_add_u64 v[4:5], s[42:43], 0, v[148:149]
	global_load_lds_dwordx4 v[4:5], off
	v_lshl_add_u64 v[4:5], s[42:43], 0, v[152:153]
	s_add_i32 m0, s45, 0x1e000
	v_lshlrev_b32_e32 v6, 2, v188
	global_load_lds_dwordx4 v[4:5], off
	s_waitcnt vmcnt(8)
	s_barrier
	v_lshlrev_b32_e32 v4, 1, v2
	v_lshl_or_b32 v5, v188, 6, v4
	v_and_b32_e32 v6, 32, v6
	v_lshl_or_b32 v189, s2, 6, v188
	v_bitop3_b32 v5, v5, s29, v6 bitop3:0xde
	v_lshlrev_b32_e32 v6, 6, v0
	s_movk_i32 s2, 0x3c0
	v_and_or_b32 v4, v6, s2, v4
	v_lshlrev_b32_e32 v6, 2, v0
	v_and_b32_e32 v6, 32, v6
	v_bitop3_b32 v190, s46, v4, v6 bitop3:0xf6
	v_lshlrev_b32_e32 v4, 8, v0
	v_and_b32_e32 v4, 0x18000, v4
	v_lshlrev_b32_e32 v6, 11, v13
	v_or3_b32 v4, v3, v4, v6
	v_add_u32_e32 v158, v4, v12
	v_lshlrev_b32_e32 v4, 4, v14
	s_waitcnt vmcnt(6)
	s_cmpk_lt_u32 s28, 0x100
	v_and_b32_e32 v4, 0x38000, v4
	s_cselect_b64 s[42:43], -1, 0
	v_lshl_or_b32 v191, s3, 6, v2
	v_and_b32_e32 v154, 16, v0
	v_or3_b32 v3, v3, v4, v6
	s_add_i32 s61, 0, 0x10000
	s_add_i32 s62, 0, 0x14000
	v_lshlrev_b32_e32 v196, 2, v2
	v_mbcnt_lo_u32_b32 v2, -1, 0
	v_or_b32_e32 v192, 0xfffffa00, v191
	s_ashr_i32 s58, s75, 31
	s_ashr_i32 s59, s96, 31
	v_lshl_add_u64 v[156:157], s[12:13], 0, v[154:155]
	v_mov_b32_e32 v159, v155
	v_add_u32_e32 v160, v3, v12
	v_mov_b32_e32 v161, v155
	v_mov_b64_e32 v[162:163], 0x200
	v_mov_b64_e32 v[164:165], 0x1ff
	v_add_u32_e32 v193, s61, v190
	v_add_u32_e32 v194, s62, v190
	v_add_u32_e32 v195, 0, v5
	v_mov_b32_e32 v197, 0x358637bd
	s_mov_b32 s63, 0xf800000
	v_mov_b32_e32 v198, 0x260
	s_movk_i32 s64, 0x4200
	v_mov_b32_e32 v199, 0x3e38aa3b
	v_mbcnt_hi_u32_b32 v200, -1, v2
	s_barrier
	s_branch .LBB0_199

; #define PG8_STAGE(bufoff, gbase, voff) do { _Pragma("unroll") for (int _i = 0; _i < 2; ++_i) \
;         __builtin_amdgcn_global_load_lds((const unsigned*)((const char*)(gbase) + (voff)[_i]), (PG8_LAS unsigned*)(lds + (bufoff) + ldsw + _i * 8192), 16, 0, 0); } while (0)
; #define PG8_WAIT_V(n) asm volatile("s_waitcnt vmcnt(" #n ")" ::: "memory")
; #define PG8_BAR __builtin_amdgcn_s_barrier()
; template <class Epi, class Sched, bool ALIGN_EPI = false, bool SP2 = false>
; __device__ __forceinline__ void gemm_phase(PG8_LAS unsigned char* lds, const Gemm g, const Sched& S, const Epi& E) {
;     ...
;     if constexpr (SP2) {
;         PG8_STAGE(PG8_SB(0, 0), cB, voffB); PG8_STAGE(PG8_SB(0, 1), cB + hstep, voffB); PG8_STAGE(PG8_SA(0, 0), cA, voffA); PG8_STAGE(PG8_SA(0, 1), cA + ahstep, voffA);
;         if (wr == 1) PG8_BAR;
;         PG8_WAIT_V(2); PG8_BAR;
;         PG8_STAGE(PG8_SB(1, 0), cB + kstep, voffB); PG8_STAGE(PG8_SA(1, 0), cA + akstep, voffA); PG8_STAGE(PG8_SB(1, 1), cB + hstep + kstep, voffB);
;         PG8_WAIT_V(6); PG8_BAR;
.LBB0_329:
	v_bfe_u32 v1, v0, 4, 2
	v_lshlrev_b32_e32 v15, 4, v1
	v_lshlrev_b32_e32 v17, 2, v18
	s_and_b32 s20, s2, 3
	v_lshl_or_b32 v16, v18, 6, v15
	s_lshl_b32 s2, s12, 13
	v_and_b32_e32 v17, 32, v17
	s_mov_b64 s[8:9], 0x80
	v_bitop3_b32 v16, v16, s2, v17 bitop3:0xde
	v_lshlrev_b32_e32 v17, 6, v0
	s_movk_i32 s2, 0x3c0
	s_add_i32 m0, s29, 0x18000
	v_lshl_add_u64 v[8:9], v[8:9], 0, s[8:9]
	v_and_or_b32 v15, v17, s2, v15
	s_lshl_b32 s2, s20, 12
	v_and_b32_e32 v17, 32, v19
	global_load_lds_dwordx4 v[8:9], off
	v_lshl_add_u64 v[6:7], v[6:7], 0, s[8:9]
	s_add_i32 m0, s29, 0x1a000
	s_add_i32 s57, s29, 0x8000
	s_add_i32 s58, s29, 0xa000
	v_bitop3_b32 v185, s2, v15, v17 bitop3:0xf6
	global_load_lds_dwordx4 v[6:7], off
	v_lshl_add_u64 v[2:3], v[2:3], 0, s[8:9]
	s_mov_b32 m0, s57
	s_add_u32 s2, s4, 0x40080
	global_load_lds_dwordx4 v[2:3], off
	v_lshl_add_u64 v[2:3], v[4:5], 0, s[8:9]
	s_mov_b32 m0, s58
	s_addc_u32 s3, s5, 0
	global_load_lds_dwordx4 v[2:3], off
	s_add_i32 m0, s29, 0x1c000
	v_lshl_add_u64 v[2:3], s[2:3], 0, v[148:149]
	global_load_lds_dwordx4 v[2:3], off
	v_lshl_add_u64 v[2:3], s[2:3], 0, v[152:153]
	s_add_i32 m0, s29, 0x1e000
	v_lshlrev_b32_e32 v14, 3, v1
	global_load_lds_dwordx4 v[2:3], off
	s_waitcnt vmcnt(8)
	s_barrier
	v_cmp_eq_u32_e64 s[2:3], 0, v1
	v_lshlrev_b32_e32 v1, 8, v0
	v_and_b32_e32 v1, 0x18000, v1
	v_lshlrev_b32_e32 v2, 11, v12
	v_or3_b32 v1, v10, v1, v2
	s_cmpk_lt_u32 s10, 0x100
	v_add_u32_e32 v158, v1, v11
	v_lshlrev_b32_e32 v1, 4, v13
	v_lshl_or_b32 v184, s12, 6, v18
	s_cselect_b64 s[10:11], -1, 0
	s_lshl_b32 s12, s12, 10
	v_and_b32_e32 v1, 0x38000, v1
	s_waitcnt vmcnt(6)
	v_lshl_or_b32 v186, s20, 6, v14
	s_ashr_i32 s59, s75, 31
	s_add_i32 s84, s12, 0
	s_mov_b32 s12, s75
	v_readlane_b32 s60, v254, 42
	v_or3_b32 v1, v10, v1, v2
	s_lshl_b32 s20, s20, 2
	s_add_i32 s6, s84, 0x20400
	v_lshlrev_b32_e32 v154, 2, v186
	v_readlane_b32 s62, v254, 44
	v_readlane_b32 s63, v254, 45
	v_readlane_b32 s68, v254, 50
	v_readlane_b32 s69, v254, 51
	v_readlane_b32 s75, v254, 57
	v_add_u32_e32 v160, v1, v11
	s_add_i32 s85, 0, 0x10000
	s_add_i32 s86, 0, 0x14000
	v_mbcnt_lo_u32_b32 v1, -1, 0
	v_lshlrev_b32_e32 v187, 4, v18
	s_ashr_i32 s97, s13, 31
	s_add_i32 s7, s6, s20
	s_add_i32 s80, s84, 0x20500
	s_add_i32 s81, s84, 0x20600
	s_add_i32 s82, s84, 0x20700
	s_add_i32 s83, s84, 0x20c00
	s_add_i32 s90, s84, 0x20d00
	s_add_i32 s91, s84, 0x20e00
	s_add_i32 s84, s84, 0x20f00
	s_mov_b32 s75, s12
	v_lshl_add_u64 v[156:157], s[68:69], 0, v[154:155]
	v_mov_b32_e32 v159, v155
	v_mov_b32_e32 v161, v155
	v_add_u32_e32 v188, s85, v185
	v_add_u32_e32 v189, s86, v185
	v_add_u32_e32 v190, 0, v16
	s_mov_b32 s12, 0x3b800000
	s_mov_b32 s87, 0xf800000
	v_mov_b32_e32 v191, 0x260
	v_mbcnt_hi_u32_b32 v192, -1, v1
	s_mov_b64 s[62:63], s[30:31]
	s_barrier
	v_readlane_b32 s61, v254, 43
	v_readlane_b32 s64, v254, 46
	v_readlane_b32 s65, v254, 47
	v_readlane_b32 s66, v254, 48
	v_readlane_b32 s67, v254, 49
	v_readlane_b32 s70, v254, 52
	v_readlane_b32 s71, v254, 53
	v_readlane_b32 s72, v254, 54
	v_readlane_b32 s73, v254, 55
	v_readlane_b32 s74, v254, 56
	s_branch .LBB0_332

; #define PG8_STAGE(bufoff, gbase, voff) do { _Pragma("unroll") for (int _i = 0; _i < 2; ++_i) \
;         __builtin_amdgcn_global_load_lds((const unsigned*)((const char*)(gbase) + (voff)[_i]), (PG8_LAS unsigned*)(lds + (bufoff) + ldsw + _i * 8192), 16, 0, 0); } while (0)
; #define PG8_WAIT_V(n) asm volatile("s_waitcnt vmcnt(" #n ")" ::: "memory")
; #define PG8_BAR __builtin_amdgcn_s_barrier()
; template <class Epi, class Sched, bool ALIGN_EPI = false, bool SP2 = false>
; __device__ __forceinline__ void gemm_phase(PG8_LAS unsigned char* lds, const Gemm g, const Sched& S, const Epi& E) {
;     ...
;     if constexpr (SP2) {
;         PG8_STAGE(PG8_SB(0, 0), cB, voffB); PG8_STAGE(PG8_SB(0, 1), cB + hstep, voffB); PG8_STAGE(PG8_SA(0, 0), cA, voffA); PG8_STAGE(PG8_SA(0, 1), cA + ahstep, voffA);
;         if (wr == 1) PG8_BAR;
;         PG8_WAIT_V(2); PG8_BAR;
;         PG8_STAGE(PG8_SB(1, 0), cB + kstep, voffB); PG8_STAGE(PG8_SA(1, 0), cA + akstep, voffA); PG8_STAGE(PG8_SB(1, 1), cB + hstep + kstep, voffB);
;         PG8_WAIT_V(6); PG8_BAR;
.LBB0_589:
	s_and_b32 s20, s10, 3
	s_mov_b64 s[10:11], 0x80
	s_add_i32 m0, s34, 0x18000
	v_lshl_add_u64 v[8:9], v[8:9], 0, s[10:11]
	s_lshl_b32 s13, s12, 13
	s_lshl_b32 s21, s20, 12
	global_load_lds_dwordx4 v[8:9], off
	v_lshl_add_u64 v[6:7], v[6:7], 0, s[10:11]
	s_add_i32 m0, s34, 0x1a000
	s_add_i32 s45, s34, 0x8000
	s_add_i32 s46, s34, 0xa000
	global_load_lds_dwordx4 v[6:7], off
	v_lshl_add_u64 v[2:3], v[2:3], 0, s[10:11]
	s_mov_b32 m0, s45
	s_add_u32 s18, s6, 0x20080
	global_load_lds_dwordx4 v[2:3], off
	v_lshl_add_u64 v[2:3], v[4:5], 0, s[10:11]
	s_mov_b32 m0, s46
	s_addc_u32 s19, s7, 0
	global_load_lds_dwordx4 v[2:3], off
	s_add_i32 m0, s34, 0x1c000
	v_lshl_add_u64 v[2:3], s[18:19], 0, v[136:137]
	global_load_lds_dwordx4 v[2:3], off
	v_lshl_add_u64 v[2:3], s[18:19], 0, v[140:141]
	s_add_i32 m0, s34, 0x1e000
	v_lshlrev_b32_e32 v4, 2, v1
	global_load_lds_dwordx4 v[2:3], off
	s_waitcnt vmcnt(8)
	s_barrier
	v_lshlrev_b32_e32 v2, 1, v13
	v_lshl_or_b32 v3, v1, 6, v2
	v_and_b32_e32 v4, 32, v4
	s_sext_i32_i8 s1, s2
	v_bitop3_b32 v3, v3, s13, v4 bitop3:0xde
	v_lshlrev_b32_e32 v4, 6, v0
	s_movk_i32 s2, 0x3c0
	v_and_or_b32 v2, v4, s2, v2
	v_lshlrev_b32_e32 v4, 2, v0
	v_and_b32_e32 v4, 32, v4
	v_bitop3_b32 v156, s21, v2, v4 bitop3:0xf6
	v_lshlrev_b32_e32 v2, 7, v0
	v_and_b32_e32 v2, 0xc000, v2
	v_lshlrev_b32_e32 v4, 10, v12
	v_or3_b32 v2, v10, v2, v4
	v_add_u32_e32 v142, v2, v11
	v_lshlrev_b32_e32 v2, 3, v14
	s_waitcnt vmcnt(6)
	s_cmpk_lt_u32 s3, 0x100
	v_and_b32_e32 v2, 0x1c000, v2
	v_lshl_or_b32 v155, s12, 6, v1
	s_cselect_b64 s[12:13], -1, 0
	v_or3_b32 v2, v10, v2, v4
	s_add_i32 s48, 0, 0x10000
	s_add_i32 s49, 0, 0x14000
	s_ashr_i32 s47, s75, 31
	v_lshl_or_b32 v157, s20, 6, v13
	v_mov_b32_e32 v143, v137
	v_add_u32_e32 v144, v2, v11
	v_mov_b32_e32 v145, v137
	v_mov_b64_e32 v[146:147], 0x80
	v_mov_b64_e32 v[148:149], 0x7f
	v_add_u32_e32 v158, s48, v156
	v_add_u32_e32 v159, s49, v156
	v_add_u32_e32 v160, 0, v3
	s_barrier
	s_branch .LBB0_592

; #define PG8_STAGE(bufoff, gbase, voff) do { _Pragma("unroll") for (int _i = 0; _i < 2; ++_i) \
;         __builtin_amdgcn_global_load_lds((const unsigned*)((const char*)(gbase) + (voff)[_i]), (PG8_LAS unsigned*)(lds + (bufoff) + ldsw + _i * 8192), 16, 0, 0); } while (0)
; #define PG8_WAIT_V(n) asm volatile("s_waitcnt vmcnt(" #n ")" ::: "memory")
; #define PG8_BAR __builtin_amdgcn_s_barrier()
; template <class Epi, class Sched, bool ALIGN_EPI = false, bool SP2 = false>
; __device__ __forceinline__ void gemm_phase(PG8_LAS unsigned char* lds, const Gemm g, const Sched& S, const Epi& E) {
;     ...
;     if constexpr (SP2) {
;         PG8_STAGE(PG8_SB(0, 0), cB, voffB); PG8_STAGE(PG8_SB(0, 1), cB + hstep, voffB); PG8_STAGE(PG8_SA(0, 0), cA, voffA); PG8_STAGE(PG8_SA(0, 1), cA + ahstep, voffA);
;         if (wr == 1) PG8_BAR;
;         PG8_WAIT_V(2); PG8_BAR;
;         PG8_STAGE(PG8_SB(1, 0), cB + kstep, voffB); PG8_STAGE(PG8_SA(1, 0), cA + akstep, voffA); PG8_STAGE(PG8_SB(1, 1), cB + hstep + kstep, voffB);
;         PG8_WAIT_V(6); PG8_BAR;
.LBB0_683:
	s_mov_b64 s[12:13], 0x80
	s_and_b32 s48, s3, 3
	s_add_i32 m0, s44, 0x18000
	v_lshl_add_u64 v[8:9], v[8:9], 0, s[12:13]
	s_lshl_b32 s3, s2, 13
	s_lshl_b32 s5, s48, 12
	global_load_lds_dwordx4 v[8:9], off
	v_lshl_add_u64 v[6:7], v[6:7], 0, s[12:13]
	s_add_i32 m0, s44, 0x1a000
	s_add_i32 s49, s44, 0x8000
	s_add_i32 s50, s44, 0xa000
	global_load_lds_dwordx4 v[6:7], off
	v_lshl_add_u64 v[2:3], v[2:3], 0, s[12:13]
	s_mov_b32 m0, s49
	s_add_u32 s14, s28, 0x40080
	global_load_lds_dwordx4 v[2:3], off
	v_lshl_add_u64 v[2:3], v[4:5], 0, s[12:13]
	s_mov_b32 m0, s50
	s_addc_u32 s15, s29, 0
	global_load_lds_dwordx4 v[2:3], off
	s_add_i32 m0, s44, 0x1c000
	v_lshl_add_u64 v[2:3], s[14:15], 0, v[180:181]
	global_load_lds_dwordx4 v[2:3], off
	v_lshl_add_u64 v[2:3], s[14:15], 0, v[184:185]
	s_add_i32 m0, s44, 0x1e000
	v_and_b32_e32 v4, 32, v20
	global_load_lds_dwordx4 v[2:3], off
	s_waitcnt vmcnt(8)
	s_barrier
	v_lshlrev_b32_e32 v2, 4, v19
	v_lshl_or_b32 v3, v18, 6, v2
	v_lshl_or_b32 v1, s2, 6, v18
	v_bitop3_b32 v3, v3, s3, v4 bitop3:0xde
	v_lshlrev_b32_e32 v4, 6, v0
	s_movk_i32 s2, 0x3c0
	v_and_or_b32 v2, v4, s2, v2
	v_lshlrev_b32_e32 v4, 2, v0
	v_and_b32_e32 v4, 32, v4
	v_bitop3_b32 v206, s5, v2, v4 bitop3:0xf6
	v_lshlrev_b32_e32 v2, 8, v0
	v_and_b32_e32 v2, 0x18000, v2
	v_lshlrev_b32_e32 v4, 11, v12
	v_or3_b32 v2, v10, v2, v4
	v_add_u32_e32 v186, v2, v11
	v_lshlrev_b32_e32 v2, 4, v13
	v_and_b32_e32 v2, 0x38000, v2
	s_waitcnt vmcnt(6)
	s_cmpk_lt_u32 s4, 0x100
	v_or3_b32 v2, v10, v2, v4
	s_cselect_b64 s[14:15], -1, 0
	v_add_u32_e32 v188, v2, v11
	s_add_i32 s53, 0, 0x10000
	s_add_i32 s54, 0, 0x14000
	v_mbcnt_lo_u32_b32 v2, -1, 0
	v_lshl_or_b32 v207, s48, 6, v21
	v_cmp_eq_u32_e64 s[2:3], 0, v19
	s_ashr_i32 s51, s75, 31
	s_ashr_i32 s52, s96, 31
	v_mov_b32_e32 v187, v181
	v_mov_b32_e32 v189, v181
	v_mov_b64_e32 v[190:191], 0x100
	v_mov_b64_e32 v[192:193], 0xff
	v_add_u32_e32 v208, s53, v206
	v_add_u32_e32 v209, s54, v206
	v_add_u32_e32 v211, 0, v3
	v_mbcnt_hi_u32_b32 v212, -1, v2
	s_mov_b32 s55, 0
	s_barrier
	s_branch .LBB0_686

; #define PG8_STAGE(bufoff, gbase, voff) do { _Pragma("unroll") for (int _i = 0; _i < 2; ++_i) \
;         __builtin_amdgcn_global_load_lds((const unsigned*)((const char*)(gbase) + (voff)[_i]), (PG8_LAS unsigned*)(lds + (bufoff) + ldsw + _i * 8192), 16, 0, 0); } while (0)
; #define PG8_WAIT_V(n) asm volatile("s_waitcnt vmcnt(" #n ")" ::: "memory")
; #define PG8_BAR __builtin_amdgcn_s_barrier()
; template <class Epi, class Sched, bool ALIGN_EPI = false, bool SP2 = false>
; __device__ __forceinline__ void gemm_phase(PG8_LAS unsigned char* lds, const Gemm g, const Sched& S, const Epi& E) {
;     ...
;     if constexpr (SP2) {
;         PG8_STAGE(PG8_SB(0, 0), cB, voffB); PG8_STAGE(PG8_SB(0, 1), cB + hstep, voffB); PG8_STAGE(PG8_SA(0, 0), cA, voffA); PG8_STAGE(PG8_SA(0, 1), cA + ahstep, voffA);
;         if (wr == 1) PG8_BAR;
;         PG8_WAIT_V(2); PG8_BAR;
;         PG8_STAGE(PG8_SB(1, 0), cB + kstep, voffB); PG8_STAGE(PG8_SA(1, 0), cA + akstep, voffA); PG8_STAGE(PG8_SB(1, 1), cB + hstep + kstep, voffB);
;         PG8_WAIT_V(6); PG8_BAR;
.LBB0_798:
	s_mov_b64 s[14:15], 0x80
	s_and_b32 s1, s4, 3
	s_add_i32 m0, s46, 0x18000
	v_lshl_add_u64 v[8:9], v[8:9], 0, s[14:15]
	s_lshl_b32 s7, s6, 6
	s_lshl_b32 s16, s6, 13
	s_lshl_b32 s17, s1, 12
	global_load_lds_dwordx4 v[8:9], off
	v_lshl_add_u64 v[6:7], v[6:7], 0, s[14:15]
	s_add_i32 m0, s46, 0x1a000
	s_add_i32 s51, s46, 0x8000
	s_add_i32 s52, s46, 0xa000
	global_load_lds_dwordx4 v[6:7], off
	v_lshl_add_u64 v[2:3], v[2:3], 0, s[14:15]
	s_mov_b32 m0, s51
	s_add_u32 s4, s30, 0x40080
	global_load_lds_dwordx4 v[2:3], off
	v_lshl_add_u64 v[2:3], v[4:5], 0, s[14:15]
	s_mov_b32 m0, s52
	s_addc_u32 s5, s31, 0
	global_load_lds_dwordx4 v[2:3], off
	s_add_i32 m0, s46, 0x1c000
	v_lshl_add_u64 v[2:3], s[4:5], 0, v[176:177]
	global_load_lds_dwordx4 v[2:3], off
	v_lshl_add_u64 v[2:3], s[4:5], 0, v[180:181]
	s_add_i32 m0, s46, 0x1e000
	v_and_b32_e32 v4, 32, v30
	global_load_lds_dwordx4 v[2:3], off
	s_waitcnt vmcnt(8)
	s_barrier
	v_lshlrev_b32_e32 v2, 4, v29
	v_lshl_or_b32 v3, v28, 6, v2
	s_sext_i32_i8 s60, s2
	v_bitop3_b32 v3, v3, s16, v4 bitop3:0xde
	v_lshlrev_b32_e32 v4, 6, v0
	s_movk_i32 s2, 0x3c0
	v_and_or_b32 v2, v4, s2, v2
	v_lshlrev_b32_e32 v4, 2, v0
	v_and_b32_e32 v5, 32, v4
	s_cmpk_lt_u32 s3, 0x100
	v_bitop3_b32 v198, s17, v2, v5 bitop3:0xf6
	s_cselect_b64 s[16:17], -1, 0
	s_lshl_b32 s6, s6, 10
	s_add_i32 s64, s6, 0
	v_lshl_or_b32 v182, s1, 6, v31
	s_lshl_b32 s1, s1, 2
	s_add_i32 s55, s64, 0x20400
	v_mov_b32_e32 v2, 0xcf
	s_ashr_i32 s53, s75, 31
	s_add_i32 s56, s55, s1
	s_mov_b32 s1, s75
	v_readlane_b32 s68, v254, 42
	v_mov_b32_e32 v183, v177
	v_bitop3_b32 v2, s7, v2, v28 bitop3:0xc8
	s_add_i32 s54, 0, 0x21400
	v_readlane_b32 s74, v254, 48
	v_readlane_b32 s75, v254, 49
	v_add_u32_e32 v200, s54, v4
	v_lshlrev_b32_e32 v4, 11, v12
	v_lshl_add_u64 v[184:185], v[182:183], 2, s[74:75]
	v_lshl_add_u32 v183, v2, 2, s54
	v_lshlrev_b32_e32 v2, 8, v0
	v_and_b32_e32 v2, 0x18000, v2
	v_or3_b32 v2, v10, v2, v4
	v_add_u32_e32 v186, v2, v11
	v_lshlrev_b32_e32 v2, 4, v13
	v_and_b32_e32 v2, 0x38000, v2
	s_waitcnt vmcnt(6)
	v_or3_b32 v2, v10, v2, v4
	s_movk_i32 s2, 0x100
	v_add_u32_e32 v188, v2, v11
	s_add_i32 s65, 0, 0x10000
	s_add_i32 s66, 0, 0x14000
	v_mbcnt_lo_u32_b32 v2, -1, 0
	v_or_b32_e32 v1, s7, v28
	v_cmp_gt_u32_e64 s[2:3], s2, v0
	v_cmp_eq_u32_e64 s[4:5], 0, v29
	v_lshlrev_b32_e32 v199, 4, v28
	s_add_i32 s57, s64, 0x20500
	s_add_i32 s58, s64, 0x20600
	s_add_i32 s59, s64, 0x20700
	s_add_i32 s61, s64, 0x20c00
	s_add_i32 s62, s64, 0x20d00
	s_add_i32 s63, s64, 0x20e00
	s_add_i32 s64, s64, 0x20f00
	s_mov_b32 s75, s1
	v_mov_b32_e32 v187, v177
	v_mov_b32_e32 v189, v177
	v_mov_b64_e32 v[190:191], 0x100
	v_mov_b64_e32 v[192:193], 0xff
	v_add_u32_e32 v201, s65, v198
	v_add_u32_e32 v202, s66, v198
	v_add_u32_e32 v203, 0, v3
	v_mov_b32_e32 v204, 0x358637bd
	s_mov_b32 s67, 0xf800000
	v_mov_b32_e32 v205, 0x260
	v_mbcnt_hi_u32_b32 v206, -1, v2
	s_mov_b32 s18, 0x3db8aa3b
	s_barrier
	v_readlane_b32 s69, v254, 43
	v_readlane_b32 s70, v254, 44
	v_readlane_b32 s71, v254, 45
	v_readlane_b32 s72, v254, 46
	v_readlane_b32 s73, v254, 47
	v_readlane_b32 s76, v254, 50
	v_readlane_b32 s77, v254, 51
	v_readlane_b32 s78, v254, 52
	v_readlane_b32 s79, v254, 53
	v_readlane_b32 s80, v254, 54
	v_readlane_b32 s81, v254, 55
	v_readlane_b32 s82, v254, 56
	v_readlane_b32 s83, v254, 57
	s_branch .LBB0_801

; #define PG8_STAGE(bufoff, gbase, voff) do { _Pragma("unroll") for (int _i = 0; _i < 2; ++_i) \
;         __builtin_amdgcn_global_load_lds((const unsigned*)((const char*)(gbase) + (voff)[_i]), (PG8_LAS unsigned*)(lds + (bufoff) + ldsw + _i * 8192), 16, 0, 0); } while (0)
; #define PG8_WAIT_V(n) asm volatile("s_waitcnt vmcnt(" #n ")" ::: "memory")
; #define PG8_BAR __builtin_amdgcn_s_barrier()
; template <class Epi, class Sched, bool ALIGN_EPI = false, bool SP2 = false>
; __device__ __forceinline__ void gemm_phase(PG8_LAS unsigned char* lds, const Gemm g, const Sched& S, const Epi& E) {
;     ...
;     if constexpr (SP2) {
;         PG8_STAGE(PG8_SB(0, 0), cB, voffB); PG8_STAGE(PG8_SB(0, 1), cB + hstep, voffB); PG8_STAGE(PG8_SA(0, 0), cA, voffA); PG8_STAGE(PG8_SA(0, 1), cA + ahstep, voffA);
;         if (wr == 1) PG8_BAR;
;         PG8_WAIT_V(2); PG8_BAR;
;         PG8_STAGE(PG8_SB(1, 0), cB + kstep, voffB); PG8_STAGE(PG8_SA(1, 0), cA + akstep, voffA); PG8_STAGE(PG8_SB(1, 1), cB + hstep + kstep, voffB);
;         PG8_WAIT_V(6); PG8_BAR;
.LBB0_966:
	s_and_b32 s46, s3, 3
	s_lshl_b32 s3, s2, 13
	s_lshl_b32 s5, s46, 12
	s_add_u32 s12, s94, 0x13200000
	s_mov_b64 s[14:15], 0x80
	s_addc_u32 s13, s95, 0
	s_add_i32 m0, s42, 0x18000
	v_lshl_add_u64 v[8:9], v[8:9], 0, s[14:15]
	global_load_lds_dwordx4 v[8:9], off
	v_lshl_add_u64 v[6:7], v[6:7], 0, s[14:15]
	s_add_i32 m0, s42, 0x1a000
	s_add_i32 s47, s42, 0x8000
	s_add_i32 s48, s42, 0xa000
	global_load_lds_dwordx4 v[6:7], off
	v_lshl_add_u64 v[2:3], v[2:3], 0, s[14:15]
	s_mov_b32 m0, s47
	s_add_u32 s16, s30, 0x40080
	global_load_lds_dwordx4 v[2:3], off
	v_lshl_add_u64 v[2:3], v[4:5], 0, s[14:15]
	s_mov_b32 m0, s48
	s_addc_u32 s17, s31, 0
	global_load_lds_dwordx4 v[2:3], off
	s_add_i32 m0, s42, 0x1c000
	v_lshl_add_u64 v[2:3], s[16:17], 0, v[156:157]
	global_load_lds_dwordx4 v[2:3], off
	v_lshl_add_u64 v[2:3], s[16:17], 0, v[160:161]
	s_add_i32 m0, s42, 0x1e000
	v_and_b32_e32 v4, 32, v20
	global_load_lds_dwordx4 v[2:3], off
	s_waitcnt vmcnt(8)
	s_barrier
	v_lshlrev_b32_e32 v2, 4, v19
	v_lshl_or_b32 v3, v18, 6, v2
	v_lshl_or_b32 v1, s2, 6, v18
	v_bitop3_b32 v3, v3, s3, v4 bitop3:0xde
	v_lshlrev_b32_e32 v4, 6, v0
	s_movk_i32 s2, 0x3c0
	v_and_or_b32 v2, v4, s2, v2
	v_lshlrev_b32_e32 v4, 2, v0
	v_and_b32_e32 v4, 32, v4
	v_bitop3_b32 v188, s5, v2, v4 bitop3:0xf6
	v_lshlrev_b32_e32 v2, 8, v0
	v_and_b32_e32 v2, 0x18000, v2
	v_lshlrev_b32_e32 v4, 11, v12
	v_or3_b32 v2, v10, v2, v4
	v_add_u32_e32 v162, v2, v11
	v_lshlrev_b32_e32 v2, 4, v13
	v_and_b32_e32 v2, 0x38000, v2
	s_waitcnt vmcnt(6)
	s_cmpk_lt_u32 s4, 0x100
	v_or3_b32 v2, v10, v2, v4
	s_cselect_b64 s[16:17], -1, 0
	v_add_u32_e32 v164, v2, v11
	s_add_i32 s51, 0, 0x10000
	s_add_i32 s52, 0, 0x14000
	v_mbcnt_lo_u32_b32 v2, -1, 0
	v_lshl_or_b32 v189, s46, 6, v21
	v_cmp_eq_u32_e64 s[2:3], 0, v19
	s_ashr_i32 s49, s75, 31
	s_ashr_i32 s50, s96, 31
	v_mov_b32_e32 v163, v157
	v_mov_b32_e32 v165, v157
	v_mov_b64_e32 v[166:167], 0x100
	v_mov_b64_e32 v[168:169], 0xff
	v_add_u32_e32 v190, s51, v188
	v_add_u32_e32 v191, s52, v188
	v_add_u32_e32 v192, 0, v3
	v_mbcnt_hi_u32_b32 v193, -1, v2
	s_mov_b32 s53, 0
	s_barrier
	s_branch .LBB0_969

; #define PG8_STAGE(bufoff, gbase, voff) do { _Pragma("unroll") for (int _i = 0; _i < 2; ++_i) \
;         __builtin_amdgcn_global_load_lds((const unsigned*)((const char*)(gbase) + (voff)[_i]), (PG8_LAS unsigned*)(lds + (bufoff) + ldsw + _i * 8192), 16, 0, 0); } while (0)
; #define PG8_WAIT_V(n) asm volatile("s_waitcnt vmcnt(" #n ")" ::: "memory")
; #define PG8_BAR __builtin_amdgcn_s_barrier()
; template <class Epi, class Sched, bool ALIGN_EPI = false, bool SP2 = false>
; __device__ __forceinline__ void gemm_phase(PG8_LAS unsigned char* lds, const Gemm g, const Sched& S, const Epi& E) {
;     ...
;     if constexpr (SP2) {
;         PG8_STAGE(PG8_SB(0, 0), cB, voffB); PG8_STAGE(PG8_SB(0, 1), cB + hstep, voffB); PG8_STAGE(PG8_SA(0, 0), cA, voffA); PG8_STAGE(PG8_SA(0, 1), cA + ahstep, voffA);
;         if (wr == 1) PG8_BAR;
;         PG8_WAIT_V(2); PG8_BAR;
;         PG8_STAGE(PG8_SB(1, 0), cB + kstep, voffB); PG8_STAGE(PG8_SA(1, 0), cA + akstep, voffA); PG8_STAGE(PG8_SB(1, 1), cB + hstep + kstep, voffB);
;         PG8_WAIT_V(6); PG8_BAR;
.LBB0_1071:
	s_and_b32 s29, s12, 3
	s_lshl_b32 s34, s64, 13
	s_lshl_b32 s35, s29, 5
	s_and_b64 s[12:13], s[30:31], exec
	s_cselect_b32 s69, 6, 5
	s_add_i32 m0, s27, 0x18000
	v_lshl_add_u64 v[2:3], v[2:3], 0, s[24:25]
	global_load_lds_dwordx4 v[2:3], off
	v_lshl_add_u64 v[2:3], v[4:5], 0, s[24:25]
	s_add_i32 m0, s27, 0x1a000
	s_add_i32 s70, s27, 0x8000
	s_add_i32 s71, s27, 0xa000
	global_load_lds_dwordx4 v[2:3], off
	v_lshl_add_u64 v[2:3], v[8:9], 0, s[24:25]
	s_mov_b32 m0, s70
	s_add_u32 s12, s38, 0x40080
	global_load_lds_dwordx4 v[2:3], off
	v_lshl_add_u64 v[2:3], v[6:7], 0, s[24:25]
	s_mov_b32 m0, s71
	s_addc_u32 s13, s39, 0
	global_load_lds_dwordx4 v[2:3], off
	s_add_i32 m0, s27, 0x1c000
	v_lshl_add_u64 v[2:3], s[12:13], 0, v[142:143]
	global_load_lds_dwordx4 v[2:3], off
	v_lshl_add_u64 v[2:3], s[12:13], 0, v[138:139]
	s_add_i32 m0, s27, 0x1e000
	s_cmpk_lt_u32 s33, 0x100
	global_load_lds_dwordx4 v[2:3], off
	s_waitcnt vmcnt(8)
	s_barrier
	s_cselect_b64 s[12:13], -1, 0
	s_lshl_b32 s72, s29, 1
	s_add_i32 s73, s64, 1
	s_cmpk_lt_u32 s33, 0x300
	s_cselect_b64 s[44:45], -1, 0
	s_cmp_eq_u32 s73, 4
	v_lshl_or_b32 v213, s29, 12, v200
	s_cselect_b64 s[46:47], -1, 0
	s_lshl_b32 s29, s64, 3
	s_or_b32 s29, s29, s72
	v_lshl_or_b32 v2, v1, 6, v199
	v_and_b32_e32 v3, 32, v207
	s_add_i32 s29, s29, 16
	s_lshl_b32 s28, s28, 7
	v_bitop3_b32 v4, v2, s34, v3 bitop3:0xde
	v_or_b32_e32 v2, s29, v203
	s_or_b32 s28, s35, s28
	v_lshlrev_b32_e32 v5, 7, v2
	v_or_b32_e32 v2, s28, v198
	v_readlane_b32 s84, v254, 0
	s_waitcnt vmcnt(6)
	s_lshl_b32 s74, s29, 7
	s_lshl_b32 s29, s64, 8
	v_ashrrev_i32_e32 v3, 31, v2
	s_ashr_i32 s30, s28, 6
	v_bitop3_b32 v6, s28, 56, v198 bitop3:0xc8
	s_add_i32 s75, s69, -1
	v_readlane_b32 s86, v254, 2
	v_readlane_b32 s87, v254, 3
	v_readlane_b32 s88, v254, 4
	v_readlane_b32 s89, v254, 5
	v_lshlrev_b64 v[2:3], 2, v[2:3]
	v_lshlrev_b32_e32 v146, 1, v6
	s_mov_b64 s[78:79], s[86:87]
	s_mov_b64 s[80:81], s[88:89]
	s_add_u32 s50, s57, s0
	v_lshl_or_b32 v212, s64, 6, v1
	v_add_u32_e32 v214, s29, v209
	v_lshl_add_u64 v[154:155], s[18:19], 0, v[2:3]
	s_mul_hi_i32 s49, s30, 0x4200
	s_mul_i32 s48, s30, 0x4200
	v_lshl_add_u64 v[156:157], s[16:17], 0, v[146:147]
	v_add_u32_e32 v146, s29, v208
	v_lshl_add_u64 v[158:159], s[78:79], 0, v[2:3]
	v_lshl_add_u64 v[160:161], s[20:21], 0, v[2:3]
	v_lshl_add_u64 v[162:163], s[22:23], 0, v[2:3]
	v_lshl_add_u64 v[164:165], s[80:81], 0, v[2:3]
	v_or_b32_e32 v215, s72, v201
	s_addc_u32 s51, s58, s1
	s_mov_b32 s76, 0
	v_add_u32_e32 v216, 0, v4
	v_add_u32_e32 v217, v204, v5
	s_barrier
	v_readlane_b32 s85, v254, 1
	v_readlane_b32 s90, v254, 6
	v_readlane_b32 s91, v254, 7
	s_branch .LBB0_1074

; #define PG8_STAGE(bufoff, gbase, voff) do { _Pragma("unroll") for (int _i = 0; _i < 2; ++_i) \
;         __builtin_amdgcn_global_load_lds((const unsigned*)((const char*)(gbase) + (voff)[_i]), (PG8_LAS unsigned*)(lds + (bufoff) + ldsw + _i * 8192), 16, 0, 0); } while (0)
; #define PG8_WAIT_V(n) asm volatile("s_waitcnt vmcnt(" #n ")" ::: "memory")
; #define PG8_BAR __builtin_amdgcn_s_barrier()
; template <class Epi, class Sched, bool ALIGN_EPI = false, bool SP2 = false>
; __device__ __forceinline__ void gemm_phase(PG8_LAS unsigned char* lds, const Gemm g, const Sched& S, const Epi& E) {
;     ...
;     if constexpr (SP2) {
;         PG8_STAGE(PG8_SB(0, 0), cB, voffB); PG8_STAGE(PG8_SB(0, 1), cB + hstep, voffB); PG8_STAGE(PG8_SA(0, 0), cA, voffA); PG8_STAGE(PG8_SA(0, 1), cA + ahstep, voffA);
;         if (wr == 1) PG8_BAR;
;         PG8_WAIT_V(2); PG8_BAR;
;         PG8_STAGE(PG8_SB(1, 0), cB + kstep, voffB); PG8_STAGE(PG8_SA(1, 0), cA + akstep, voffA); PG8_STAGE(PG8_SB(1, 1), cB + hstep + kstep, voffB);
;         PG8_WAIT_V(6); PG8_BAR;
.LBB0_1187:
	s_mov_b64 s[10:11], 0x80
	s_and_b32 s3, s3, 3
	s_add_i32 m0, s21, 0x18000
	v_lshl_add_u64 v[4:5], v[4:5], 0, s[10:11]
	s_lshl_b32 s14, s0, 13
	s_lshl_b32 s15, s3, 12
	global_load_lds_dwordx4 v[4:5], off
	s_add_i32 m0, s21, 0x1a000
	s_add_u32 s12, s24, 0x210000
	v_lshl_add_u64 v[2:3], v[2:3], 0, s[10:11]
	s_addc_u32 s13, s25, 0
	s_add_i32 s37, s21, 0x8000
	global_load_lds_dwordx4 v[2:3], off
	v_lshl_add_u64 v[2:3], s[12:13], 0, v[128:129]
	s_mov_b32 m0, s37
	s_add_i32 s38, s21, 0xa000
	global_load_lds_dwordx4 v[2:3], off
	v_lshl_add_u64 v[2:3], s[12:13], 0, v[132:133]
	s_add_u32 s12, s22, 0xb0080
	s_mov_b32 m0, s38
	s_addc_u32 s13, s23, 0
	global_load_lds_dwordx4 v[2:3], off
	s_add_i32 m0, s21, 0x1c000
	v_lshl_add_u64 v[2:3], s[12:13], 0, v[130:131]
	global_load_lds_dwordx4 v[2:3], off
	v_lshl_add_u64 v[2:3], s[12:13], 0, v[134:135]
	s_add_i32 m0, s21, 0x1e000
	v_lshl_or_b32 v152, s0, 6, v1
	global_load_lds_dwordx4 v[2:3], off
	s_waitcnt vmcnt(8)
	s_barrier
	v_lshlrev_b32_e32 v2, 1, v10
	v_lshl_or_b32 v3, v1, 6, v2
	v_lshlrev_b32_e32 v1, 2, v1
	v_and_b32_e32 v1, 32, v1
	v_bitop3_b32 v1, v3, s14, v1 bitop3:0xde
	v_lshlrev_b32_e32 v3, 6, v0
	s_movk_i32 s0, 0x3c0
	v_lshlrev_b32_e32 v0, 2, v0
	v_and_or_b32 v2, v3, s0, v2
	v_and_b32_e32 v0, 32, v0
	v_bitop3_b32 v153, s15, v2, v0 bitop3:0xf6
	v_and_b32_e32 v0, 0x1800, v8
	v_lshlrev_b32_e32 v2, 7, v9
	v_or3_b32 v0, v6, v0, v2
	s_waitcnt vmcnt(6)
	s_cmpk_lt_u32 s2, 0x100
	v_add_u32_e32 v136, v0, v7
	v_and_b32_e32 v0, 0x3800, v11
	s_cselect_b64 s[12:13], -1, 0
	v_or3_b32 v0, v6, v0, v2
	s_add_i32 s40, 0, 0x10000
	s_add_i32 s41, 0, 0x14000
	s_sext_i32_i8 s43, s1
	s_ashr_i32 s39, s75, 31
	v_lshl_or_b32 v154, s3, 6, v10
	v_mov_b32_e32 v137, v131
	v_add_u32_e32 v138, v0, v7
	v_mov_b32_e32 v139, v131
	v_mov_b64_e32 v[140:141], 0x100
	v_mov_b64_e32 v[142:143], 0xff
	v_add_u32_e32 v155, s40, v153
	v_add_u32_e32 v156, s41, v153
	v_add_u32_e32 v157, 0, v1
	s_barrier
	s_branch .LBB0_1190
